# P7 epilogue: hoist 8 ss row-scale loads, drop per-step vmcnt(0)
# speedup vs baseline: 1.0000x; 1.0000x over previous
; __device__ __forceinline__ u32x4 pack8(f32x4 a, f32x4 b) { u32x4 w; w[0] = cvt_pk_bf16(a[0], a[1]); w[1] = cvt_pk_bf16(a[2], a[3]); w[2] = cvt_pk_bf16(b[0], b[1]); w[3] = cvt_pk_bf16(b[2], b[3]); return w; }
;   __device__ __forceinline__ void operator()(const Acc& acc, const GUnit& u, int wr, int wc, int fr, int fq) const {
;     const int row0 = u.pm * 256 + wr * 64 + fr;
;     bf16_t* ob = (u.pn < nsplit ? O0 + (size_t)u.pn * 256 : O1 + (size_t)(u.pn - nsplit) * 256) + wc * 32 + 8 * fq;
; #pragma unroll
;     for (int ai = 0; ai < 2; ++ai)
; #pragma unroll
;       for (int m = 0; m < 4; ++m) {
;         const int row = row0 + ai * 128 + m * 16;
;         const float rs = ss ? rsqrtf(ss[row] * (1.f / 2048.f) + EPS) : 1.f;
; #pragma unroll
;         for (int bj = 0; bj < 2; ++bj) *(u32x4*)(ob + (size_t)row * ld + bj * 128) = pack8(acc[ai][bj][m][0] * rs, acc[ai][bj][m][1] * rs);
;       }
.LBB0_1128:
	v_mov_b32_e32 v132, v200
	s_lshl_b32 s4, s48, 8
	v_readfirstlane_b32 s26, v132
	s_ashr_i32 s5, s26, 2
	s_andn2_b32 s5, s5, 63
	s_add_i32 s5, s5, s4
	v_and_or_b32 v138, v132, 15, s5
	v_ashrrev_i32_e32 v139, 31, v138
	v_lshl_add_u64 v[134:135], v[138:139], 2, s[8:9]
	global_load_dword v145, v[134:135], off
	global_load_dword v210, v[134:135], off offset:64
	global_load_dword v211, v[134:135], off offset:128
	global_load_dword v212, v[134:135], off offset:192
	global_load_dword v213, v[134:135], off offset:512
	global_load_dword v214, v[134:135], off offset:576
	global_load_dword v215, v[134:135], off offset:640
	global_load_dword v216, v[134:135], off offset:704
	v_readlane_b32 s28, v254, 16
	s_add_i32 s4, s49, -16
	s_ashr_i32 s5, s49, 31
	v_readlane_b32 s29, v254, 17
	s_cmp_lt_i32 s49, 16
	v_readlane_b32 s28, v254, 38
	v_lshlrev_b64 v[136:137], 13, v[138:139]
	s_cselect_b32 s5, s5, 0
	s_cselect_b32 s4, s49, s4
	v_readlane_b32 s30, v254, 18
	v_readlane_b32 s31, v254, 19
	v_readlane_b32 s29, v254, 39
	s_cselect_b32 s27, s31, s29
	s_cselect_b32 s28, s30, s28
	s_lshl_b64 s[4:5], s[4:5], 9
	s_add_u32 s4, s28, s4
	s_addc_u32 s5, s27, s5
	s_and_b32 s26, s26, 0xc0
	s_add_u32 s4, s4, s26
	v_and_b32_e32 v132, 48, v132
	s_addc_u32 s5, s5, 0
	v_lshl_add_u64 v[150:151], s[4:5], 0, v[132:133]
	v_or_b32_e32 v146, 16, v138
	v_ashrrev_i32_e32 v147, 31, v146
	v_lshl_add_u64 v[136:137], v[150:151], 0, v[136:137]
	v_lshl_add_u64 v[148:149], v[146:147], 2, s[8:9]
	s_waitcnt vmcnt(0)
	v_fmamk_f32 v139, v145, 0x3a000000, v144
	v_mul_f32_e32 v145, 0x4b800000, v139
	v_cmp_gt_f32_e32 vcc, s41, v139
	s_nop 1
	v_cndmask_b32_e32 v139, v139, v145, vcc
	v_rsq_f32_e32 v139, v139
	s_nop 0
	v_mul_f32_e32 v132, 0x45800000, v139
	v_cndmask_b32_e32 v132, v139, v132, vcc
	v_pk_mul_f32 v[126:127], v[126:127], v[132:133] op_sel_hi:[1,0]
	v_pk_mul_f32 v[124:125], v[124:125], v[132:133] op_sel_hi:[1,0]
	v_pk_mul_f32 v[122:123], v[122:123], v[132:133] op_sel_hi:[1,0]
	v_pk_mul_f32 v[120:121], v[120:121], v[132:133] op_sel_hi:[1,0]
	v_pk_mul_f32 v[118:119], v[118:119], v[132:133] op_sel_hi:[1,0]
	v_pk_mul_f32 v[116:117], v[116:117], v[132:133] op_sel_hi:[1,0]
	v_pk_mul_f32 v[152:153], v[114:115], v[132:133] op_sel_hi:[1,0]
	v_pk_mul_f32 v[154:155], v[112:113], v[132:133] op_sel_hi:[1,0]
	v_cvt_pk_bf16_f32 v112, v124, v125
	v_cvt_pk_bf16_f32 v113, v126, v127
	v_cvt_pk_bf16_f32 v114, v120, v121
	v_cvt_pk_bf16_f32 v115, v122, v123
	v_cvt_pk_bf16_f32 v116, v116, v117
	v_cvt_pk_bf16_f32 v117, v118, v119
	s_nop 0
	v_cvt_pk_bf16_f32 v118, v154, v155
	v_cvt_pk_bf16_f32 v119, v152, v153
	global_store_dwordx4 v[136:137], v[112:115], off
	global_store_dwordx4 v[136:137], v[116:119], off offset:256
	s_nop 0
	v_or_b32_e32 v112, 32, v138
	v_ashrrev_i32_e32 v113, 31, v112
	v_lshl_add_u64 v[116:117], v[112:113], 2, s[8:9]
	v_fmamk_f32 v114, v210, 0x3a000000, v144
	v_mul_f32_e32 v115, 0x4b800000, v114
	v_cmp_gt_f32_e32 vcc, s41, v114
	s_nop 1
	v_cndmask_b32_e32 v114, v114, v115, vcc
	v_rsq_f32_e32 v118, v114
	v_lshlrev_b64 v[114:115], 13, v[146:147]
	v_lshl_add_u64 v[114:115], v[150:151], 0, v[114:115]
	v_mul_f32_e32 v119, 0x45800000, v118
	v_cndmask_b32_e32 v118, v118, v119, vcc
	v_pk_mul_f32 v[110:111], v[110:111], v[118:119] op_sel_hi:[1,0]
	v_pk_mul_f32 v[108:109], v[108:109], v[118:119] op_sel_hi:[1,0]
	v_pk_mul_f32 v[106:107], v[106:107], v[118:119] op_sel_hi:[1,0]
	v_pk_mul_f32 v[104:105], v[104:105], v[118:119] op_sel_hi:[1,0]
	v_pk_mul_f32 v[102:103], v[102:103], v[118:119] op_sel_hi:[1,0]
	v_pk_mul_f32 v[100:101], v[100:101], v[118:119] op_sel_hi:[1,0]
	v_pk_mul_f32 v[120:121], v[98:99], v[118:119] op_sel_hi:[1,0]
	v_pk_mul_f32 v[118:119], v[96:97], v[118:119] op_sel_hi:[1,0]
	v_cvt_pk_bf16_f32 v96, v108, v109
	v_cvt_pk_bf16_f32 v97, v110, v111
	v_cvt_pk_bf16_f32 v98, v104, v105
	v_cvt_pk_bf16_f32 v99, v106, v107
	v_cvt_pk_bf16_f32 v100, v100, v101
	v_cvt_pk_bf16_f32 v101, v102, v103
	s_nop 0
	v_cvt_pk_bf16_f32 v102, v118, v119
	v_cvt_pk_bf16_f32 v103, v120, v121
	global_store_dwordx4 v[114:115], v[96:99], off
	global_store_dwordx4 v[114:115], v[100:103], off offset:256
	s_nop 0
	v_or_b32_e32 v96, 48, v138
	v_ashrrev_i32_e32 v97, 31, v96
	v_lshl_add_u64 v[100:101], v[96:97], 2, s[8:9]
	v_fmamk_f32 v98, v211, 0x3a000000, v144
	v_mul_f32_e32 v99, 0x4b800000, v98
	v_cmp_gt_f32_e32 vcc, s41, v98
	s_nop 1
	v_cndmask_b32_e32 v98, v98, v99, vcc
	v_rsq_f32_e32 v102, v98
	v_lshlrev_b64 v[98:99], 13, v[112:113]
	v_lshl_add_u64 v[98:99], v[150:151], 0, v[98:99]
	v_mul_f32_e32 v103, 0x45800000, v102
	v_cndmask_b32_e32 v102, v102, v103, vcc
	v_pk_mul_f32 v[94:95], v[94:95], v[102:103] op_sel_hi:[1,0]
	v_pk_mul_f32 v[92:93], v[92:93], v[102:103] op_sel_hi:[1,0]
	v_pk_mul_f32 v[90:91], v[90:91], v[102:103] op_sel_hi:[1,0]
	v_pk_mul_f32 v[88:89], v[88:89], v[102:103] op_sel_hi:[1,0]
	v_pk_mul_f32 v[86:87], v[86:87], v[102:103] op_sel_hi:[1,0]
	v_pk_mul_f32 v[84:85], v[84:85], v[102:103] op_sel_hi:[1,0]
	v_pk_mul_f32 v[104:105], v[82:83], v[102:103] op_sel_hi:[1,0]
	v_pk_mul_f32 v[102:103], v[80:81], v[102:103] op_sel_hi:[1,0]
	v_cvt_pk_bf16_f32 v80, v92, v93
	v_cvt_pk_bf16_f32 v81, v94, v95
	v_cvt_pk_bf16_f32 v82, v88, v89
	v_cvt_pk_bf16_f32 v83, v90, v91
	v_cvt_pk_bf16_f32 v84, v84, v85
	v_cvt_pk_bf16_f32 v85, v86, v87
	s_nop 0
	v_cvt_pk_bf16_f32 v86, v102, v103
	v_cvt_pk_bf16_f32 v87, v104, v105
	global_store_dwordx4 v[98:99], v[80:83], off
	global_store_dwordx4 v[98:99], v[84:87], off offset:256
	s_nop 0
	v_fmamk_f32 v80, v212, 0x3a000000, v144
	v_mul_f32_e32 v81, 0x4b800000, v80
	v_cmp_gt_f32_e32 vcc, s41, v80
	s_nop 1
	v_cndmask_b32_e32 v80, v80, v81, vcc
	v_rsq_f32_e32 v82, v80
; __device__ __forceinline__ u32x4 pack8(f32x4 a, f32x4 b) { u32x4 w; w[0] = cvt_pk_bf16(a[0], a[1]); w[1] = cvt_pk_bf16(a[2], a[3]); w[2] = cvt_pk_bf16(b[0], b[1]); w[3] = cvt_pk_bf16(b[2], b[3]); return w; }
; #define G8_BAR __builtin_amdgcn_s_barrier()
;     ...
;     if (!has_next) break;
; #pragma unroll
;     for (int a = 0; a < 2; ++a)
; #pragma unroll
;       for (int b = 0; b < 2; ++b)
; #pragma unroll
;         for (int m = 0; m < 4; ++m)
; #pragma unroll
;           for (int n = 0; n < 2; ++n) acc[a][b][m][n] = (f32x4){0.f, 0.f, 0.f, 0.f};
;     cur = nxt; cA = nA; cB = nB; ++ui;
;     if (wr == 1) G8_BAR;
;   __device__ __forceinline__ void operator()(const Acc& acc, const GUnit& u, int wr, int wc, int fr, int fq) const {
;     const int row0 = u.pm * 256 + wr * 64 + fr;
;     bf16_t* ob = (u.pn < nsplit ? O0 + (size_t)u.pn * 256 : O1 + (size_t)(u.pn - nsplit) * 256) + wc * 32 + 8 * fq;
; #pragma unroll
;     for (int ai = 0; ai < 2; ++ai)
; #pragma unroll
;       for (int m = 0; m < 4; ++m) {
;         const int row = row0 + ai * 128 + m * 16;
;         const float rs = ss ? rsqrtf(ss[row] * (1.f / 2048.f) + EPS) : 1.f;
; #pragma unroll
;         for (int bj = 0; bj < 2; ++bj) *(u32x4*)(ob + (size_t)row * ld + bj * 128) = pack8(acc[ai][bj][m][0] * rs, acc[ai][bj][m][1] * rs);
;       }
	v_lshlrev_b64 v[80:81], 13, v[96:97]
	v_lshl_add_u64 v[80:81], v[150:151], 0, v[80:81]
	v_mul_f32_e32 v83, 0x45800000, v82
	v_cndmask_b32_e32 v82, v82, v83, vcc
	v_pk_mul_f32 v[78:79], v[78:79], v[82:83] op_sel_hi:[1,0]
	v_pk_mul_f32 v[76:77], v[76:77], v[82:83] op_sel_hi:[1,0]
	v_pk_mul_f32 v[74:75], v[74:75], v[82:83] op_sel_hi:[1,0]
	v_pk_mul_f32 v[72:73], v[72:73], v[82:83] op_sel_hi:[1,0]
	v_pk_mul_f32 v[70:71], v[70:71], v[82:83] op_sel_hi:[1,0]
	v_pk_mul_f32 v[68:69], v[68:69], v[82:83] op_sel_hi:[1,0]
	v_pk_mul_f32 v[84:85], v[66:67], v[82:83] op_sel_hi:[1,0]
	v_pk_mul_f32 v[82:83], v[64:65], v[82:83] op_sel_hi:[1,0]
	v_cvt_pk_bf16_f32 v64, v76, v77
	v_cvt_pk_bf16_f32 v65, v78, v79
	v_cvt_pk_bf16_f32 v66, v72, v73
	v_cvt_pk_bf16_f32 v67, v74, v75
	v_cvt_pk_bf16_f32 v68, v68, v69
	v_cvt_pk_bf16_f32 v69, v70, v71
	s_nop 0
	v_cvt_pk_bf16_f32 v70, v82, v83
	v_cvt_pk_bf16_f32 v71, v84, v85
	global_store_dwordx4 v[80:81], v[64:67], off
	global_store_dwordx4 v[80:81], v[68:71], off offset:256
	s_nop 0
	v_lshl_add_u64 v[64:65], v[136:137], 0, s[14:15]
	v_fmamk_f32 v66, v213, 0x3a000000, v144
	v_mul_f32_e32 v67, 0x4b800000, v66
	v_cmp_gt_f32_e32 vcc, s41, v66
	s_nop 1
	v_cndmask_b32_e32 v66, v66, v67, vcc
	v_rsq_f32_e32 v68, v66
	v_add_co_u32_e64 v66, s[4:5], s42, v136
	v_mul_f32_e32 v69, 0x45800000, v68
	v_cndmask_b32_e32 v68, v68, v69, vcc
	v_addc_co_u32_e64 v67, s[4:5], 0, v137, s[4:5]
	v_pk_mul_f32 v[62:63], v[62:63], v[68:69] op_sel_hi:[1,0]
	v_pk_mul_f32 v[60:61], v[60:61], v[68:69] op_sel_hi:[1,0]
	v_pk_mul_f32 v[58:59], v[58:59], v[68:69] op_sel_hi:[1,0]
	v_pk_mul_f32 v[56:57], v[56:57], v[68:69] op_sel_hi:[1,0]
	v_pk_mul_f32 v[54:55], v[54:55], v[68:69] op_sel_hi:[1,0]
	v_pk_mul_f32 v[52:53], v[52:53], v[68:69] op_sel_hi:[1,0]
	v_pk_mul_f32 v[70:71], v[50:51], v[68:69] op_sel_hi:[1,0]
	v_pk_mul_f32 v[68:69], v[48:49], v[68:69] op_sel_hi:[1,0]
	v_cvt_pk_bf16_f32 v48, v60, v61
	v_cvt_pk_bf16_f32 v49, v62, v63
	v_cvt_pk_bf16_f32 v50, v56, v57
	v_cvt_pk_bf16_f32 v51, v58, v59
	v_cvt_pk_bf16_f32 v52, v52, v53
	v_cvt_pk_bf16_f32 v53, v54, v55
	s_nop 0
	v_cvt_pk_bf16_f32 v54, v68, v69
	v_cvt_pk_bf16_f32 v55, v70, v71
	global_store_dwordx4 v[66:67], v[48:51], off
	global_store_dwordx4 v[64:65], v[52:55], off offset:256
	s_nop 0
	v_lshl_add_u64 v[48:49], v[136:137], 0, s[16:17]
	v_fmamk_f32 v50, v214, 0x3a000000, v144
	v_mul_f32_e32 v51, 0x4b800000, v50
	v_cmp_gt_f32_e32 vcc, s41, v50
	s_nop 1
	v_cndmask_b32_e32 v50, v50, v51, vcc
	v_rsq_f32_e32 v52, v50
	v_add_co_u32_e64 v50, s[4:5], s43, v136
	v_mul_f32_e32 v53, 0x45800000, v52
	v_cndmask_b32_e32 v52, v52, v53, vcc
	v_addc_co_u32_e64 v51, s[4:5], 0, v137, s[4:5]
	v_pk_mul_f32 v[46:47], v[46:47], v[52:53] op_sel_hi:[1,0]
	v_pk_mul_f32 v[44:45], v[44:45], v[52:53] op_sel_hi:[1,0]
	v_pk_mul_f32 v[42:43], v[42:43], v[52:53] op_sel_hi:[1,0]
	v_pk_mul_f32 v[40:41], v[40:41], v[52:53] op_sel_hi:[1,0]
	v_pk_mul_f32 v[38:39], v[38:39], v[52:53] op_sel_hi:[1,0]
	v_pk_mul_f32 v[36:37], v[36:37], v[52:53] op_sel_hi:[1,0]
	v_pk_mul_f32 v[54:55], v[34:35], v[52:53] op_sel_hi:[1,0]
	v_pk_mul_f32 v[52:53], v[32:33], v[52:53] op_sel_hi:[1,0]
	v_cvt_pk_bf16_f32 v32, v44, v45
	v_cvt_pk_bf16_f32 v33, v46, v47
	v_cvt_pk_bf16_f32 v34, v40, v41
	v_cvt_pk_bf16_f32 v35, v42, v43
	v_cvt_pk_bf16_f32 v36, v36, v37
	v_cvt_pk_bf16_f32 v37, v38, v39
	s_nop 0
	v_cvt_pk_bf16_f32 v38, v52, v53
	v_cvt_pk_bf16_f32 v39, v54, v55
	global_store_dwordx4 v[50:51], v[32:35], off
	global_store_dwordx4 v[48:49], v[36:39], off offset:256
	s_nop 0
	v_lshl_add_u64 v[32:33], v[136:137], 0, s[18:19]
	v_fmamk_f32 v34, v215, 0x3a000000, v144
	v_mul_f32_e32 v35, 0x4b800000, v34
	v_cmp_gt_f32_e32 vcc, s41, v34
	s_nop 1
	v_cndmask_b32_e32 v34, v34, v35, vcc
	v_rsq_f32_e32 v36, v34
	v_add_co_u32_e64 v34, s[4:5], s44, v136
	v_mul_f32_e32 v37, 0x45800000, v36
	v_cndmask_b32_e32 v36, v36, v37, vcc
	v_addc_co_u32_e64 v35, s[4:5], 0, v137, s[4:5]
	v_pk_mul_f32 v[30:31], v[30:31], v[36:37] op_sel_hi:[1,0]
	v_pk_mul_f32 v[28:29], v[28:29], v[36:37] op_sel_hi:[1,0]
	v_pk_mul_f32 v[26:27], v[26:27], v[36:37] op_sel_hi:[1,0]
	v_pk_mul_f32 v[24:25], v[24:25], v[36:37] op_sel_hi:[1,0]
	v_pk_mul_f32 v[22:23], v[22:23], v[36:37] op_sel_hi:[1,0]
	v_pk_mul_f32 v[20:21], v[20:21], v[36:37] op_sel_hi:[1,0]
	v_pk_mul_f32 v[38:39], v[18:19], v[36:37] op_sel_hi:[1,0]
	v_pk_mul_f32 v[36:37], v[16:17], v[36:37] op_sel_hi:[1,0]
	v_cvt_pk_bf16_f32 v16, v28, v29
	v_cvt_pk_bf16_f32 v17, v30, v31
	v_cvt_pk_bf16_f32 v18, v24, v25
	v_cvt_pk_bf16_f32 v19, v26, v27
	v_cvt_pk_bf16_f32 v20, v20, v21
	v_cvt_pk_bf16_f32 v21, v22, v23
	s_nop 0
	v_cvt_pk_bf16_f32 v22, v36, v37
	v_cvt_pk_bf16_f32 v23, v38, v39
	global_store_dwordx4 v[34:35], v[16:19], off
	global_store_dwordx4 v[32:33], v[20:23], off offset:256
	s_nop 0
	s_andn2_b64 vcc, exec, s[6:7]
	v_lshl_add_u64 v[16:17], v[136:137], 0, s[20:21]
	v_fmamk_f32 v18, v216, 0x3a000000, v144
	v_mul_f32_e32 v19, 0x4b800000, v18
	v_cmp_gt_f32_e64 s[4:5], s41, v18
	s_nop 1
	v_cndmask_b32_e64 v18, v18, v19, s[4:5]
	v_rsq_f32_e32 v20, v18
	v_add_co_u32_e64 v18, s[6:7], s45, v136
	v_mul_f32_e32 v21, 0x45800000, v20
	v_cndmask_b32_e64 v20, v20, v21, s[4:5]
	v_addc_co_u32_e64 v19, s[6:7], 0, v137, s[6:7]
	v_pk_mul_f32 v[14:15], v[14:15], v[20:21] op_sel_hi:[1,0]
	v_pk_mul_f32 v[12:13], v[12:13], v[20:21] op_sel_hi:[1,0]
	v_pk_mul_f32 v[10:11], v[10:11], v[20:21] op_sel_hi:[1,0]
	v_pk_mul_f32 v[8:9], v[8:9], v[20:21] op_sel_hi:[1,0]
	v_pk_mul_f32 v[6:7], v[6:7], v[20:21] op_sel_hi:[1,0]
	v_pk_mul_f32 v[4:5], v[4:5], v[20:21] op_sel_hi:[1,0]
	v_pk_mul_f32 v[22:23], v[2:3], v[20:21] op_sel_hi:[1,0]
	v_pk_mul_f32 v[20:21], v[0:1], v[20:21] op_sel_hi:[1,0]
	v_cvt_pk_bf16_f32 v0, v12, v13
	v_cvt_pk_bf16_f32 v1, v14, v15
	v_cvt_pk_bf16_f32 v2, v8, v9
	v_cvt_pk_bf16_f32 v3, v10, v11
	s_mov_b64 s[4:5], -1
	v_cvt_pk_bf16_f32 v4, v4, v5
	v_cvt_pk_bf16_f32 v5, v6, v7
	v_cvt_pk_bf16_f32 v6, v20, v21
	v_cvt_pk_bf16_f32 v7, v22, v23
	global_store_dwordx4 v[18:19], v[0:3], off
	global_store_dwordx4 v[16:17], v[4:7], off offset:256
	s_cbranch_vccnz .LBB0_1117
	s_andn2_b64 vcc, exec, s[10:11]
	s_cbranch_vccnz .LBB0_1116
	s_barrier
	s_branch .LBB0_1116
